# prologue modulation GEMM: the five row tiles of a weight slab placed on one XCD (slab-major block order)
# speedup vs baseline: 1.0016x; 1.0016x over previous
; #define LAS __attribute__((address_space(3)))
; #define MOD_LOAD(W) do { _Pragma("unroll") for (int kk = 0; kk < 32; ++kk) { W[kk] = *wp; wp += 2 * NMOD; asm volatile("" : "+v"(wp)); } } while (0)
; __device__ __forceinline__ void p0_prologue(Frame& F) {
;     ...
;         const int rt = blk / 48, sgp = blk % 48, r32 = lane & 31, hi = lane >> 5;
;         LAS float* SC = (LAS float*)(F.lds + RING_OFF);
;         for (int i = tid; i < 32768; i += NWAVES * 64) { const int j = i >> 10, k = i & 1023; int R = rt * 32 + j; R = R < 144 ? R : 143;
;             const float c = R < NBATCH ? c_prompt[R * DM + k] : c_sample[(R - NBATCH) * DM + k]; SC[k * 32 + j] = c / (1.f + expf(-c)); }
;         __syncthreads();
;         const int s = F.wave & 3, kh = F.wave >> 2, col = (sgp * 4 + s) * 32 + r32;
;         f32x16 acc;
; #pragma unroll
;         for (int r = 0; r < 16; ++r) acc[r] = 0.f;
;         const float* wp = w_mod + (size_t)(kh * 512 + hi) * NMOD + col;
;         const LAS float* ap = SC + (kh * 512 + hi) * 32 + r32;
;     ...
;         float wA[32], wB[32];
;         MOD_LOAD(wA);
.LBB0_30:
	s_or_b64 exec, exec, s[36:37]
	s_mul_i32 s4, s81, 0xcccd
	s_lshr_b32 s4, s4, 18
	s_bfe_u32 s6, s76, 0x20006
	s_lshl_b32 s4, s4, 7
	s_lshl_b32 s5, s6, 5
	v_and_b32_e32 v4, 31, v1
	v_ashrrev_i32_e32 v19, 5, v1
	s_or_b32 s4, s4, s5
	s_lshr_b32 s7, s76, 8
	v_or_b32_e32 v20, s4, v4
	v_lshl_add_u32 v5, s7, 9, v19
	s_movk_i32 s4, 0x6000
	s_waitcnt lgkmcnt(0)
	v_mov_b64_e32 v[2:3], s[34:35]
	v_mad_i64_i32 v[2:3], s[4:5], v5, s4, v[2:3]
	v_ashrrev_i32_e32 v21, 31, v20
	v_lshl_add_u64 v[2:3], v[20:21], 2, v[2:3]
	s_mov_b64 s[4:5], 0xc000
	s_barrier
	global_load_dword v24, v[2:3], off
	v_lshl_add_u64 v[2:3], v[2:3], 0, s[4:5]
	global_load_dword v25, v[2:3], off
	v_lshl_add_u64 v[2:3], v[2:3], 0, s[4:5]
	global_load_dword v26, v[2:3], off
	v_lshl_add_u64 v[2:3], v[2:3], 0, s[4:5]
	global_load_dword v27, v[2:3], off
	v_lshl_add_u64 v[2:3], v[2:3], 0, s[4:5]
	global_load_dword v29, v[2:3], off
	v_lshl_add_u64 v[2:3], v[2:3], 0, s[4:5]
	global_load_dword v31, v[2:3], off
	v_lshl_add_u64 v[2:3], v[2:3], 0, s[4:5]
	global_load_dword v33, v[2:3], off
	v_lshl_add_u64 v[2:3], v[2:3], 0, s[4:5]
	global_load_dword v35, v[2:3], off
	v_lshl_add_u64 v[2:3], v[2:3], 0, s[4:5]
	global_load_dword v32, v[2:3], off
	v_lshl_add_u64 v[2:3], v[2:3], 0, s[4:5]
	global_load_dword v36, v[2:3], off
	v_lshl_add_u64 v[2:3], v[2:3], 0, s[4:5]
	global_load_dword v37, v[2:3], off
	v_lshl_add_u64 v[2:3], v[2:3], 0, s[4:5]
	global_load_dword v39, v[2:3], off
	v_lshl_add_u64 v[2:3], v[2:3], 0, s[4:5]
	global_load_dword v40, v[2:3], off
	v_lshl_add_u64 v[2:3], v[2:3], 0, s[4:5]
	global_load_dword v42, v[2:3], off
	v_lshl_add_u64 v[2:3], v[2:3], 0, s[4:5]
	global_load_dword v43, v[2:3], off
	v_lshl_add_u64 v[2:3], v[2:3], 0, s[4:5]
	global_load_dword v46, v[2:3], off
	v_lshl_add_u64 v[2:3], v[2:3], 0, s[4:5]
	global_load_dword v44, v[2:3], off
	v_lshl_add_u64 v[2:3], v[2:3], 0, s[4:5]
	global_load_dword v47, v[2:3], off
	v_lshl_add_u64 v[2:3], v[2:3], 0, s[4:5]
	global_load_dword v48, v[2:3], off
	v_lshl_add_u64 v[2:3], v[2:3], 0, s[4:5]
	global_load_dword v50, v[2:3], off
	v_lshl_add_u64 v[2:3], v[2:3], 0, s[4:5]
	global_load_dword v51, v[2:3], off
	v_lshl_add_u64 v[2:3], v[2:3], 0, s[4:5]
	global_load_dword v53, v[2:3], off
	v_lshl_add_u64 v[2:3], v[2:3], 0, s[4:5]
	global_load_dword v55, v[2:3], off
	v_lshl_add_u64 v[2:3], v[2:3], 0, s[4:5]
	global_load_dword v56, v[2:3], off
	v_lshl_add_u64 v[2:3], v[2:3], 0, s[4:5]
	global_load_dword v54, v[2:3], off
	v_lshl_add_u64 v[2:3], v[2:3], 0, s[4:5]
	global_load_dword v52, v[2:3], off
	v_lshl_add_u64 v[2:3], v[2:3], 0, s[4:5]
	global_load_dword v49, v[2:3], off
	v_lshl_add_u64 v[2:3], v[2:3], 0, s[4:5]
	global_load_dword v45, v[2:3], off
	v_lshl_add_u64 v[2:3], v[2:3], 0, s[4:5]
	global_load_dword v41, v[2:3], off
	v_lshl_add_u64 v[2:3], v[2:3], 0, s[4:5]
	global_load_dword v38, v[2:3], off
	v_lshl_add_u64 v[2:3], v[2:3], 0, s[4:5]
	global_load_dword v34, v[2:3], off
	v_lshl_add_u64 v[2:3], v[2:3], 0, s[4:5]
	global_load_dword v30, v[2:3], off
	v_lshlrev_b32_e32 v5, 7, v5
	v_lshl_add_u64 v[22:23], v[2:3], 0, s[4:5]
	v_lshlrev_b32_e32 v2, 2, v4
	v_add3_u32 v28, 0, v5, v2
	v_mov_b32_e32 v2, 0
	s_movk_i32 s8, 0xffc0
	v_mov_b32_e32 v3, v2
	v_mov_b32_e32 v4, v2
	v_mov_b32_e32 v5, v2
	v_mov_b32_e32 v6, v2
	v_mov_b32_e32 v7, v2
	v_mov_b32_e32 v8, v2
	v_mov_b32_e32 v9, v2
	v_mov_b32_e32 v10, v2
	v_mov_b32_e32 v11, v2
	v_mov_b32_e32 v12, v2
	v_mov_b32_e32 v13, v2
	v_mov_b32_e32 v14, v2
	v_mov_b32_e32 v15, v2
	v_mov_b32_e32 v16, v2
	v_mov_b32_e32 v17, v2
